# on the previous stack: attention step-boundary scalars moved in front of the closing wait (nothing but the branch after the barrier), row-max canonicalisation 3 VALU -> 1, no-op LDS base add removed
# speedup vs baseline: 1.0278x; 1.0017x over previous
.LBB0_274:
	s_add_i32 s10, s44, 0xfffe8000
	s_and_b32 s10, s10, 0x10000
	v_add_u32_e32 v237, s10, v222
	v_add_u32_e32 v80, v237, v223
	v_add_u32_e32 v236, s10, v233
	s_and_b32 s11, s44, 0x18000
	s_add_i32 s11, s93, s11
	ds_read_b128 v[96:99], v80 offset:32768
	ds_read_b128 v[184:187], v80 offset:40960
	v_add_u32_e32 v80, v237, v225
	ds_read_b128 v[180:183], v80 offset:32768
	ds_read_b128 v[176:179], v80 offset:40960
	v_add_u32_e32 v80, v236, v228
	ds_read_b128 v[172:175], v80 offset:16384
	ds_read_b128 v[168:171], v80 offset:20480
	ds_read_b128 v[164:167], v80 offset:24576
	ds_read_b128 v[160:163], v80 offset:28672
	v_mov_b32_e32 v80, v190
	s_nop 1
	v_permlane32_swap_b32_e32 v190, v80
	v_cmp_lt_f32_e32 vcc, s13, v190
	s_cbranch_vccz .LBB0_276
	v_max_f32_e32 v64, v190, v190
	v_max_f32_e32 v65, 0, v64
	v_exp_f32_e64 v80, -v65
	v_add_f32_e32 v229, v229, v65
	v_xor_b32_e32 v64, 0x80000000, v229
	v_sub_f32_e32 v127, v127, v65
	v_sub_f32_e32 v126, v126, v65
	v_sub_f32_e32 v125, v125, v65
	v_sub_f32_e32 v124, v124, v65
	v_sub_f32_e32 v123, v123, v65
	v_sub_f32_e32 v122, v122, v65
	v_sub_f32_e32 v121, v121, v65
	v_sub_f32_e32 v120, v120, v65
	v_sub_f32_e32 v119, v119, v65
	v_sub_f32_e32 v118, v118, v65
	v_sub_f32_e32 v117, v117, v65
	v_sub_f32_e32 v116, v116, v65
	v_sub_f32_e32 v115, v115, v65
	v_sub_f32_e32 v114, v114, v65
	v_sub_f32_e32 v113, v113, v65
	v_sub_f32_e32 v112, v112, v65
	v_sub_f32_e32 v143, v143, v65
	v_sub_f32_e32 v142, v142, v65
	v_sub_f32_e32 v141, v141, v65
	v_sub_f32_e32 v140, v140, v65
	v_sub_f32_e32 v139, v139, v65
	v_sub_f32_e32 v138, v138, v65
	v_sub_f32_e32 v137, v137, v65
	v_sub_f32_e32 v136, v136, v65
	v_sub_f32_e32 v135, v135, v65
	v_sub_f32_e32 v134, v134, v65
	v_sub_f32_e32 v133, v133, v65
	v_sub_f32_e32 v132, v132, v65
	v_sub_f32_e32 v131, v131, v65
	v_sub_f32_e32 v130, v130, v65
	v_sub_f32_e32 v129, v129, v65
	v_sub_f32_e32 v128, v128, v65
	v_mov_b32_e32 v65, v64
	v_mov_b32_e32 v66, v64
	v_mov_b32_e32 v67, v64
	v_mov_b32_e32 v68, v64
	v_mov_b32_e32 v69, v64
	v_mov_b32_e32 v70, v64
	v_mov_b32_e32 v71, v64
	v_mov_b32_e32 v72, v64
	v_mov_b32_e32 v73, v64
	v_mov_b32_e32 v74, v64
	v_mov_b32_e32 v75, v64
	v_mov_b32_e32 v76, v64
	v_mov_b32_e32 v77, v64
	v_mov_b32_e32 v78, v64
	v_mov_b32_e32 v79, v64
	v_pk_mul_f32 v[62:63], v[62:63], v[80:81] op_sel_hi:[1,0]
	v_pk_mul_f32 v[60:61], v[60:61], v[80:81] op_sel_hi:[1,0]
	v_pk_mul_f32 v[58:59], v[58:59], v[80:81] op_sel_hi:[1,0]
	v_pk_mul_f32 v[56:57], v[56:57], v[80:81] op_sel_hi:[1,0]
	v_pk_mul_f32 v[54:55], v[54:55], v[80:81] op_sel_hi:[1,0]
	v_pk_mul_f32 v[52:53], v[52:53], v[80:81] op_sel_hi:[1,0]
	v_pk_mul_f32 v[50:51], v[50:51], v[80:81] op_sel_hi:[1,0]
	v_pk_mul_f32 v[48:49], v[48:49], v[80:81] op_sel_hi:[1,0]
	v_pk_mul_f32 v[46:47], v[46:47], v[80:81] op_sel_hi:[1,0]
	v_pk_mul_f32 v[44:45], v[44:45], v[80:81] op_sel_hi:[1,0]
	v_pk_mul_f32 v[42:43], v[42:43], v[80:81] op_sel_hi:[1,0]
	v_pk_mul_f32 v[40:41], v[40:41], v[80:81] op_sel_hi:[1,0]
	v_pk_mul_f32 v[38:39], v[38:39], v[80:81] op_sel_hi:[1,0]
	v_pk_mul_f32 v[36:37], v[36:37], v[80:81] op_sel_hi:[1,0]
	v_pk_mul_f32 v[34:35], v[34:35], v[80:81] op_sel_hi:[1,0]
	v_pk_mul_f32 v[32:33], v[32:33], v[80:81] op_sel_hi:[1,0]
	v_pk_mul_f32 v[14:15], v[14:15], v[80:81] op_sel_hi:[1,0]
	v_pk_mul_f32 v[12:13], v[12:13], v[80:81] op_sel_hi:[1,0]
	v_pk_mul_f32 v[10:11], v[10:11], v[80:81] op_sel_hi:[1,0]
	v_pk_mul_f32 v[8:9], v[8:9], v[80:81] op_sel_hi:[1,0]
	v_pk_mul_f32 v[6:7], v[6:7], v[80:81] op_sel_hi:[1,0]
	v_pk_mul_f32 v[4:5], v[4:5], v[80:81] op_sel_hi:[1,0]
	v_pk_mul_f32 v[2:3], v[2:3], v[80:81] op_sel_hi:[1,0]
	v_pk_mul_f32 v[0:1], v[0:1], v[80:81] op_sel_hi:[1,0]
	v_pk_mul_f32 v[30:31], v[30:31], v[80:81] op_sel_hi:[1,0]
	v_pk_mul_f32 v[28:29], v[28:29], v[80:81] op_sel_hi:[1,0]
	v_pk_mul_f32 v[26:27], v[26:27], v[80:81] op_sel_hi:[1,0]
	v_pk_mul_f32 v[24:25], v[24:25], v[80:81] op_sel_hi:[1,0]
	v_pk_mul_f32 v[22:23], v[22:23], v[80:81] op_sel_hi:[1,0]
	v_pk_mul_f32 v[20:21], v[20:21], v[80:81] op_sel_hi:[1,0]
	v_pk_mul_f32 v[18:19], v[18:19], v[80:81] op_sel_hi:[1,0]
	v_pk_mul_f32 v[16:17], v[16:17], v[80:81] op_sel_hi:[1,0]
	v_pk_mul_f32 v[188:189], v[188:189], v[80:81] op_sel_hi:[1,0]

.Latt_dA3:
	v_mfma_f32_32x32x16_bf16 v[48:63], v[172:175], v[188:191], v[48:63]
	v_exp_f32_e32 v132, v132
	v_exp_f32_e32 v133, v133
	v_add_f32_e32 v172, v132, v237
	v_add_f32_e32 v173, v133, v219
	v_mfma_f32_32x32x16_bf16 v[32:47], v[168:171], v[188:191], v[32:47]
	v_exp_f32_e32 v134, v134
	v_exp_f32_e32 v135, v135
	v_add_f32_e32 v168, v134, v172
	v_add_f32_e32 v169, v135, v173
	v_mfma_f32_32x32x16_bf16 v[0:15], v[164:167], v[188:191], v[0:15]
	v_exp_f32_e32 v136, v136
	v_exp_f32_e32 v137, v137
	v_cvt_pk_bf16_f32 v164, v128, v129
	v_cvt_pk_bf16_f32 v165, v130, v131
	v_add_f32_e32 v166, v136, v168
	v_add_f32_e32 v167, v137, v169
	v_mfma_f32_32x32x16_bf16 v[16:31], v[160:163], v[188:191], v[16:31]
	v_exp_f32_e32 v138, v138
	v_exp_f32_e32 v139, v139
	v_add_f32_e32 v160, v138, v166
	v_add_f32_e32 v161, v139, v167
	v_cvt_pk_bf16_f32 v166, v132, v133
	v_cvt_pk_bf16_f32 v167, v134, v135
	v_exp_f32_e32 v140, v140
	v_exp_f32_e32 v141, v141
	s_waitcnt lgkmcnt(0)
	v_mfma_f32_32x32x16_bf16 v[48:63], v[238:241], v[176:179], v[48:63]
	v_add_u32_e32 v190, v236, v231
	v_add_f32_e32 v172, v140, v160
	v_add_f32_e32 v173, v141, v161
	ds_read_b128 v[160:163], v190 offset:16384
	ds_read_b128 v[168:171], v190 offset:20480
	v_exp_f32_e32 v142, v142
	v_exp_f32_e32 v143, v143
	v_mfma_f32_32x32x16_bf16 v[32:47], v[194:197], v[176:179], v[32:47]
	v_add_f32_e32 v189, v142, v172
	v_add_f32_e32 v188, v143, v173
	ds_read_b128 v[172:175], v190 offset:24576
	ds_read_b128 v[194:197], v190 offset:28672
	v_mfma_f32_32x32x16_bf16 v[0:15], v[184:187], v[176:179], v[0:15]
	v_cvt_pk_bf16_f32 v184, v136, v137
	v_cvt_pk_bf16_f32 v185, v138, v139
	v_mfma_f32_32x32x16_bf16 v[16:31], v[180:183], v[176:179], v[16:31]
	v_cvt_pk_bf16_f32 v186, v140, v141
	v_cvt_pk_bf16_f32 v187, v142, v143
	s_waitcnt lgkmcnt(0)
	v_mfma_f32_32x32x16_bf16 v[48:63], v[160:163], v[164:167], v[48:63]
	v_add_u32_e32 v180, v236, v232
	ds_read_b128 v[160:163], v180 offset:16384
	ds_read_b128 v[176:179], v180 offset:20480
	v_max_f32_e32 v190, v80, v96
	v_max3_f32 v191, v97, v82, v98
	v_mfma_f32_32x32x16_bf16 v[32:47], v[168:171], v[164:167], v[32:47]
	ds_read_b128 v[168:171], v180 offset:24576
	ds_read_b128 v[180:183], v180 offset:28672
	v_max3_f32 v190, v190, v81, v83
	v_max3_f32 v191, v191, v84, v100
	v_mfma_f32_32x32x16_bf16 v[0:15], v[172:175], v[164:167], v[0:15]
	v_max3_f32 v172, v190, v99, v85
	v_max3_f32 v173, v191, v86, v102
	v_mfma_f32_32x32x16_bf16 v[16:31], v[194:197], v[164:167], v[16:31]
	v_max3_f32 v164, v172, v101, v87
	v_max3_f32 v165, v173, v88, v104
	s_waitcnt lgkmcnt(0)
	v_mfma_f32_32x32x16_bf16 v[48:63], v[160:163], v[184:187], v[48:63]
	v_max3_f32 v160, v164, v103, v89
	v_max3_f32 v161, v165, v90, v106
	v_mfma_f32_32x32x16_bf16 v[32:47], v[176:179], v[184:187], v[32:47]
	v_max3_f32 v160, v160, v105, v91
	v_max3_f32 v161, v161, v92, v108
	v_mfma_f32_32x32x16_bf16 v[0:15], v[168:171], v[184:187], v[0:15]
	v_max3_f32 v160, v160, v107, v93
	v_max3_f32 v161, v161, v94, v110
	v_mfma_f32_32x32x16_bf16 v[16:31], v[180:183], v[184:187], v[16:31]
	v_max3_f32 v160, v160, v109, v95
	v_max3_f32 v190, v160, v111, v161
	s_mov_b64 s[80:81], -1
	s_and_b64 vcc, exec, s[38:39]
	s_cbranch_vccnz .LBB0_277
	s_add_i32 s10, s96, 6
	s_cmp_le_u32 s10, s94
	s_cselect_b64 s[38:39], -1, 0
	s_cmp_ge_u32 s45, s95
	s_waitcnt vmcnt(4) lgkmcnt(0)
	s_barrier
	s_cbranch_scc1 .LBB0_268

; __device__ __forceinline__ void attn_unit2(LAS unsigned char* lds, const bf16_t* Q, const bf16_t* K, const bf16_t* VT, bf16_t* Y, const float* subg, float lam, float outscale, int b, int h, int qb, int wid0) {
;     ...
;     for (int t = 0; t < nta; t += 2) {
;         A2_STEP(sA, sB, nA, nB, t);
;         A2_STEP(nA, nB, sA, sB, t + 1);
.Latt_dB3:
	v_mfma_f32_32x32x16_bf16 v[48:63], v[172:175], v[188:191], v[48:63]
	v_exp_f32_e32 v100, v100
	v_exp_f32_e32 v101, v101
	v_add_f32_e32 v172, v100, v209
	v_add_f32_e32 v173, v101, v210
	v_mfma_f32_32x32x16_bf16 v[32:47], v[168:171], v[188:191], v[32:47]
	v_exp_f32_e32 v102, v102
	v_exp_f32_e32 v103, v103
	v_add_f32_e32 v168, v102, v172
	v_add_f32_e32 v169, v103, v173
	v_mfma_f32_32x32x16_bf16 v[0:15], v[164:167], v[188:191], v[0:15]
	v_exp_f32_e32 v104, v104
	v_exp_f32_e32 v105, v105
	v_cvt_pk_bf16_f32 v164, v96, v97
	v_cvt_pk_bf16_f32 v165, v98, v99
	v_add_f32_e32 v166, v104, v168
	v_add_f32_e32 v167, v105, v169
	v_mfma_f32_32x32x16_bf16 v[16:31], v[160:163], v[188:191], v[16:31]
	v_exp_f32_e32 v106, v106
	v_exp_f32_e32 v107, v107
	v_add_f32_e32 v160, v106, v166
	v_add_f32_e32 v161, v107, v167
	v_cvt_pk_bf16_f32 v166, v100, v101
	v_cvt_pk_bf16_f32 v167, v102, v103
	v_exp_f32_e32 v108, v108
	v_exp_f32_e32 v109, v109
	s_waitcnt lgkmcnt(0)
	v_mfma_f32_32x32x16_bf16 v[48:63], v[194:197], v[176:179], v[48:63]
	v_add_u32_e32 v190, v208, v231
	v_add_f32_e32 v172, v108, v160
	v_add_f32_e32 v173, v109, v161
	ds_read_b128 v[160:163], v190 offset:49152
	ds_read_b128 v[168:171], v190 offset:53248
	v_exp_f32_e32 v110, v110
	v_exp_f32_e32 v111, v111
	v_mfma_f32_32x32x16_bf16 v[32:47], v[244:247], v[176:179], v[32:47]
	v_add_f32_e32 v189, v110, v172
	v_add_f32_e32 v188, v111, v173
	ds_read_b128 v[172:175], v190 offset:57344
	ds_read_b128 v[194:197], v190 offset:61440
	v_mfma_f32_32x32x16_bf16 v[0:15], v[184:187], v[176:179], v[0:15]
	v_cvt_pk_bf16_f32 v184, v104, v105
	v_cvt_pk_bf16_f32 v185, v106, v107
	v_mfma_f32_32x32x16_bf16 v[16:31], v[180:183], v[176:179], v[16:31]
	v_cvt_pk_bf16_f32 v186, v108, v109
	v_cvt_pk_bf16_f32 v187, v110, v111
	s_waitcnt lgkmcnt(0)
	v_mfma_f32_32x32x16_bf16 v[48:63], v[160:163], v[164:167], v[48:63]
	v_add_u32_e32 v180, v208, v232
	ds_read_b128 v[160:163], v180 offset:49152
	ds_read_b128 v[176:179], v180 offset:53248
	v_max_f32_e32 v190, v112, v128
	v_max3_f32 v191, v129, v114, v130
	v_mfma_f32_32x32x16_bf16 v[32:47], v[168:171], v[164:167], v[32:47]
	ds_read_b128 v[168:171], v180 offset:57344
	ds_read_b128 v[180:183], v180 offset:61440
	v_max3_f32 v190, v190, v113, v115
	v_max3_f32 v191, v191, v116, v132
	v_mfma_f32_32x32x16_bf16 v[0:15], v[172:175], v[164:167], v[0:15]
	v_max3_f32 v172, v190, v131, v117
	v_max3_f32 v173, v191, v118, v134
	v_mfma_f32_32x32x16_bf16 v[16:31], v[194:197], v[164:167], v[16:31]
	v_max3_f32 v164, v172, v133, v119
	v_max3_f32 v165, v173, v120, v136
	s_waitcnt lgkmcnt(0)
	v_mfma_f32_32x32x16_bf16 v[48:63], v[160:163], v[184:187], v[48:63]
	v_max3_f32 v160, v164, v135, v121
	v_max3_f32 v161, v165, v122, v138
	v_mfma_f32_32x32x16_bf16 v[32:47], v[176:179], v[184:187], v[32:47]
	v_max3_f32 v160, v160, v137, v123
	v_max3_f32 v161, v161, v124, v140
	v_mfma_f32_32x32x16_bf16 v[0:15], v[168:171], v[184:187], v[0:15]
	v_max3_f32 v160, v160, v139, v125
	v_max3_f32 v161, v161, v126, v142
	v_mfma_f32_32x32x16_bf16 v[16:31], v[180:183], v[184:187], v[16:31]
	v_max3_f32 v160, v160, v141, v127
	v_max3_f32 v190, v160, v143, v161
	s_andn2_b64 vcc, exec, s[38:39]
	s_mov_b64 s[38:39], -1
	s_cbranch_vccnz .LBB0_269
.LBB0_282:
	s_add_i32 s44, s44, 0x10000
	s_cmp_ge_u32 s45, s94
	s_cbranch_scc1 .Latt_exit_pre
	s_mov_b32 s96, s45
	s_add_i32 s10, s96, 5
	s_cmp_ge_u32 s10, s22
	s_cselect_b64 s[38:39], -1, 0
	s_add_i32 s45, s96, 2
	s_cmp_gt_u32 s45, s95
	s_waitcnt vmcnt(4) lgkmcnt(0)
	s_barrier
	s_cbranch_scc0 .LBB0_274
	s_branch .LBB0_263
.Latt_exit_pre:
	s_waitcnt vmcnt(4) lgkmcnt(0)
	s_barrier
